# kv up-projection tiles handed out in reverse CU order to balance with the q up-projection (no grid sync between them)
# baseline (speedup 1.0000x reference)
.LBB0_651:
	s_cmp_eq_u32 s78, 3
	s_cbranch_scc0 .Lkv_norev
	s_sub_i32 s0, s28, 1
	s_sub_i32 s59, s0, s59
	s_and_b32 s0, s59, 7
	v_writelane_b32 v253, s0, 4
	s_lshr_b32 s0, s59, 3
	v_writelane_b32 v253, s0, 5

.LBB0_715:
	v_readlane_b32 s59, v253, 45
	s_nop 3
	s_and_b32 s0, s59, 7
	v_writelane_b32 v253, s0, 4
	s_lshr_b32 s1, s59, 3
	v_writelane_b32 v253, s1, 5
	s_nop 1
	v_readlane_b32 s0, v255, 4
	v_readlane_b32 s1, v255, 5
	s_xor_b64 s[0:1], s[0:1], -1
	v_readlane_b32 s34, v253, 60
	v_readlane_b32 s36, v253, 62
	v_readlane_b32 s38, v254, 0
	v_readlane_b32 s40, v254, 2
	v_readlane_b32 s42, v254, 4
	v_readlane_b32 s44, v254, 6
	v_readlane_b32 s46, v254, 8
	v_readlane_b32 s48, v254, 10
	v_readlane_b32 s50, v254, 12
	v_readlane_b32 s52, v254, 14
	s_andn2_b64 vcc, exec, s[0:1]
	s_mov_b64 s[0:1], -1
	v_readlane_b32 s35, v253, 61
	v_readlane_b32 s37, v253, 63
	v_readlane_b32 s39, v254, 1
	v_readlane_b32 s41, v254, 3
	v_readlane_b32 s43, v254, 5
	v_readlane_b32 s45, v254, 7
	v_readlane_b32 s47, v254, 9
	v_readlane_b32 s49, v254, 11
	v_readlane_b32 s51, v254, 13
	v_readlane_b32 s53, v254, 15
	s_cbranch_vccnz .LBB0_765
	s_waitcnt vmcnt(0)
	s_waitcnt vmcnt(0) lgkmcnt(0)
	s_barrier
	s_mov_b64 s[0:1], exec
	v_readlane_b32 s2, v251, 2
	v_readlane_b32 s3, v251, 3
	s_and_b64 s[2:3], s[0:1], s[2:3]
	s_mov_b64 exec, s[2:3]
	s_cbranch_execz .LBB0_764
	v_readlane_b32 s2, v253, 37
	s_waitcnt vmcnt(0) expcnt(0) lgkmcnt(0)
	s_nop 0
	v_mov_b32_e32 v0, s2
	ds_read_b32 v2, v0
	v_readlane_b32 s2, v253, 38
	s_waitcnt lgkmcnt(0)
	v_cmp_ne_u32_e32 vcc, 0, v2
	v_mov_b32_e32 v0, s2
	ds_read_b32 v0, v0
	s_cbranch_vccnz .LBB0_732
	s_mov_b32 s10, 1
	s_branch .LBB0_720
